# no-setprio K-loops + residual epilogues (out-proj, down L0): 16 stream-tile loads issued up front with counted vmcnt instead of load/vmcnt(0)/store ladder
# baseline (speedup 1.0000x reference)
.LBB0_875:
	v_and_b32_e32 v148, 64, v235
	v_xor_b32_e32 v145, 16, v235
	v_add_u32_e32 v148, 64, v148
	v_cmp_lt_i32_e32 vcc, v145, v148
	v_lshl_add_u32 v144, s50, 8, v151
	v_lshl_or_b32 v146, s49, 8, v153
	v_cndmask_b32_e32 v145, v235, v145, vcc
	v_lshlrev_b32_e32 v156, 2, v145
	v_xor_b32_e32 v145, 32, v235
	v_cmp_lt_i32_e32 vcc, v145, v148
	v_ashrrev_i32_e32 v147, 31, v146
	v_mov_b32_e32 v168, v126
	v_cndmask_b32_e32 v145, v235, v145, vcc
	v_lshlrev_b32_e32 v155, 2, v145
	v_ashrrev_i32_e32 v145, 31, v144
	v_lshlrev_b64 v[148:149], 13, v[144:145]
	v_lshl_add_u64 v[158:159], s[4:5], 0, v[148:149]
	v_lshlrev_b64 v[148:149], 1, v[146:147]
	v_lshl_add_u64 v[146:147], v[158:159], 0, v[148:149]
	global_load_dwordx4 v[158:161], v[146:147], off
	global_load_dwordx4 v[162:165], v[146:147], off offset:256
	s_mov_b64 s[100:101], 0x20000
	v_lshl_add_u64 v[224:225], v[146:147], 0, s[100:101]
	global_load_dwordx4 v[172:175], v[224:225], off
	global_load_dwordx4 v[176:179], v[224:225], off offset:256
	s_mov_b64 s[100:101], 0x40000
	v_lshl_add_u64 v[224:225], v[146:147], 0, s[100:101]
	global_load_dwordx4 v[180:183], v[224:225], off
	global_load_dwordx4 v[184:187], v[224:225], off offset:256
	s_mov_b64 s[100:101], 0x60000
	v_lshl_add_u64 v[224:225], v[146:147], 0, s[100:101]
	global_load_dwordx4 v[188:191], v[224:225], off
	global_load_dwordx4 v[192:195], v[224:225], off offset:256
	s_mov_b64 s[100:101], 0x100000
	v_lshl_add_u64 v[224:225], v[146:147], 0, s[100:101]
	global_load_dwordx4 v[196:199], v[224:225], off
	global_load_dwordx4 v[200:203], v[224:225], off offset:256
	s_mov_b64 s[100:101], 0x120000
	v_lshl_add_u64 v[224:225], v[146:147], 0, s[100:101]
	global_load_dwordx4 v[204:207], v[224:225], off
	global_load_dwordx4 v[208:211], v[224:225], off offset:256
	s_mov_b64 s[100:101], 0x140000
	v_lshl_add_u64 v[224:225], v[146:147], 0, s[100:101]
	global_load_dwordx4 v[216:219], v[224:225], off
	global_load_dwordx4 v[220:223], v[224:225], off offset:256
	s_mov_b64 s[100:101], 0x160000
	v_lshl_add_u64 v[224:225], v[146:147], 0, s[100:101]
	global_load_dwordx4 v[242:245], v[224:225], off
	global_load_dwordx4 v[246:249], v[224:225], off offset:256
	v_mov_b32_e32 v169, v118
	v_mov_b32_e32 v118, v127
	v_mov_b32_e32 v171, v120
	v_mov_b32_e32 v120, v129
	v_mov_b32_e32 v170, v128
	s_mov_b32 s9, 0x100000
	s_mov_b64 s[24:25], 0x100000
	s_waitcnt vmcnt(14)
	v_lshlrev_b32_e32 v166, 16, v158
	v_lshlrev_b32_e32 v167, 16, v162
	v_pk_add_f32 v[166:167], v[168:169], v[166:167]
	v_and_b32_e32 v169, 0xffff0000, v162
	v_and_b32_e32 v168, 0xffff0000, v158
	v_pk_add_f32 v[126:127], v[118:119], v[168:169]
	v_lshlrev_b32_e32 v169, 16, v163
	v_and_b32_e32 v163, 0xffff0000, v163
	v_and_b32_e32 v162, 0xffff0000, v159
	v_lshlrev_b32_e32 v168, 16, v159
	v_pk_add_f32 v[128:129], v[120:121], v[162:163]
	v_lshlrev_b32_e32 v121, 16, v164
	v_lshlrev_b32_e32 v120, 16, v160
	v_mov_b32_e32 v158, v122
	v_mov_b32_e32 v159, v114
	v_pk_add_f32 v[158:159], v[158:159], v[120:121]
	v_and_b32_e32 v121, 0xffff0000, v164
	v_and_b32_e32 v120, 0xffff0000, v160
	v_mov_b32_e32 v114, v123
	v_pk_add_f32 v[122:123], v[114:115], v[120:121]
	v_lshlrev_b32_e32 v115, 16, v165
	v_lshlrev_b32_e32 v114, 16, v161
	v_mov_b32_e32 v162, v124
	v_mov_b32_e32 v163, v116
	v_pk_add_f32 v[162:163], v[162:163], v[114:115]
	v_and_b32_e32 v115, 0xffff0000, v165
	v_and_b32_e32 v114, 0xffff0000, v161
	v_mov_b32_e32 v116, v125
	v_pk_add_f32 v[168:169], v[170:171], v[168:169]
	v_pk_add_f32 v[124:125], v[116:117], v[114:115]
	v_cvt_pk_bf16_f32 v114, v167, v127
	v_cvt_pk_bf16_f32 v115, v169, v129
	v_cvt_pk_bf16_f32 v116, v159, v123
	v_cvt_pk_bf16_f32 v117, v163, v125
	global_store_dwordx4 v[146:147], v[114:117], off offset:256
	v_cvt_pk_bf16_f32 v118, v166, v126
	v_cvt_pk_bf16_f32 v119, v168, v128
	v_pk_mul_f32 v[114:115], v[126:127], v[126:127]
	v_pk_mul_f32 v[116:117], v[128:129], v[128:129]
	v_cvt_pk_bf16_f32 v120, v158, v122
	v_cvt_pk_bf16_f32 v121, v162, v124
	v_pk_fma_f32 v[114:115], v[166:167], v[166:167], v[114:115]
	v_pk_fma_f32 v[116:117], v[168:169], v[168:169], v[116:117]
	global_store_dwordx4 v[146:147], v[118:121], off
	v_pk_add_f32 v[114:115], v[114:115], v[116:117]
	v_pk_mul_f32 v[116:117], v[122:123], v[122:123]
	v_pk_mul_f32 v[118:119], v[124:125], v[124:125]
	v_pk_fma_f32 v[116:117], v[158:159], v[158:159], v[116:117]
	v_pk_fma_f32 v[118:119], v[162:163], v[162:163], v[118:119]
	s_nop 0
	v_pk_add_f32 v[116:117], v[116:117], v[118:119]
	s_nop 0
	v_pk_add_f32 v[114:115], v[114:115], v[116:117]
	v_or_b32_e32 v116, 16, v144
	v_ashrrev_i32_e32 v117, 31, v116
	v_lshlrev_b64 v[116:117], 13, v[116:117]
	v_lshl_add_u64 v[116:117], s[4:5], 0, v[116:117]
	v_lshl_add_u64 v[120:121], v[116:117], 0, v[148:149]
	v_add_f32_e32 v114, v114, v115
	ds_bpermute_b32 v115, v156, v114
	s_waitcnt lgkmcnt(0)
	v_add_f32_e32 v114, v114, v115
	ds_bpermute_b32 v115, v155, v114
	s_waitcnt vmcnt(15)
	v_mov_b32_e32 v116, v172
	v_mov_b32_e32 v117, v173
	v_mov_b32_e32 v118, v174
	v_mov_b32_e32 v119, v175
	v_lshlrev_b32_e32 v122, 16, v116
	v_and_b32_e32 v123, 0xffff0000, v116
	v_lshlrev_b32_e32 v116, 16, v117
	v_and_b32_e32 v117, 0xffff0000, v117
	v_pk_add_f32 v[112:113], v[112:113], v[116:117]
	v_lshlrev_b32_e32 v116, 16, v118
	v_and_b32_e32 v117, 0xffff0000, v118
	v_pk_add_f32 v[116:117], v[106:107], v[116:117]
	v_lshlrev_b32_e32 v106, 16, v119
	v_and_b32_e32 v107, 0xffff0000, v119
	v_pk_add_f32 v[110:111], v[110:111], v[122:123]
	v_pk_add_f32 v[118:119], v[108:109], v[106:107]
	v_cvt_pk_bf16_f32 v106, v110, v111
	v_cvt_pk_bf16_f32 v107, v112, v113
	v_cvt_pk_bf16_f32 v108, v116, v117
	v_cvt_pk_bf16_f32 v109, v118, v119
	global_store_dwordx4 v[120:121], v[106:109], off
	v_pk_mul_f32 v[116:117], v[116:117], v[116:117]
	v_pk_mul_f32 v[118:119], v[118:119], v[118:119]
	v_pk_mul_f32 v[110:111], v[110:111], v[110:111]
	v_pk_mul_f32 v[112:113], v[112:113], v[112:113]
	s_waitcnt vmcnt(15)
	v_mov_b32_e32 v106, v176
	v_mov_b32_e32 v107, v177
	v_mov_b32_e32 v108, v178
	v_mov_b32_e32 v109, v179
	v_lshlrev_b32_e32 v122, 16, v106
	v_and_b32_e32 v123, 0xffff0000, v106
	v_lshlrev_b32_e32 v106, 16, v107
	v_and_b32_e32 v107, 0xffff0000, v107
	v_pk_add_f32 v[104:105], v[104:105], v[106:107]
	v_lshlrev_b32_e32 v106, 16, v108
	v_and_b32_e32 v107, 0xffff0000, v108
	v_pk_add_f32 v[106:107], v[98:99], v[106:107]
	v_lshlrev_b32_e32 v98, 16, v109
	v_and_b32_e32 v99, 0xffff0000, v109
	v_pk_add_f32 v[102:103], v[102:103], v[122:123]
	v_pk_add_f32 v[108:109], v[100:101], v[98:99]
	v_cvt_pk_bf16_f32 v98, v102, v103
	v_cvt_pk_bf16_f32 v99, v104, v105
	v_cvt_pk_bf16_f32 v100, v106, v107
	v_cvt_pk_bf16_f32 v101, v108, v109
	global_store_dwordx4 v[120:121], v[98:101], off offset:256
	s_nop 1
	v_pk_mul_f32 v[98:99], v[102:103], v[102:103]
	v_pk_mul_f32 v[100:101], v[104:105], v[104:105]
	v_add_f32_e32 v98, v98, v99
	v_add_f32_e32 v100, v100, v101
	v_pk_mul_f32 v[102:103], v[106:107], v[106:107]
	v_pk_mul_f32 v[104:105], v[108:109], v[108:109]
	v_add_f32_e32 v98, v98, v100
	v_add_f32_e32 v99, v118, v119
	v_add_f32_e32 v100, v116, v117
	v_add_f32_e32 v104, v104, v105
	v_add_f32_e32 v102, v102, v103
	v_add_f32_e32 v99, v100, v99
	v_add_f32_e32 v100, v112, v113
	v_add_f32_e32 v101, v110, v111
	v_add_f32_e32 v102, v102, v104
	v_add_f32_e32 v100, v101, v100
	v_add_f32_e32 v98, v98, v102
	v_add_f32_e32 v99, v100, v99
	v_add_f32_e32 v98, v99, v98
	ds_bpermute_b32 v99, v156, v98
	s_waitcnt lgkmcnt(0)
	v_add_f32_e32 v100, v98, v99
	v_or_b32_e32 v98, 32, v144
	v_ashrrev_i32_e32 v99, 31, v98
	v_lshlrev_b64 v[98:99], 13, v[98:99]
	v_lshl_add_u64 v[98:99], s[4:5], 0, v[98:99]
	v_lshl_add_u64 v[98:99], v[98:99], 0, v[148:149]
	ds_bpermute_b32 v101, v155, v100
	s_waitcnt vmcnt(15)
	v_mov_b32_e32 v102, v180
	v_mov_b32_e32 v103, v181
	v_mov_b32_e32 v104, v182
	v_mov_b32_e32 v105, v183
	v_lshlrev_b32_e32 v106, 16, v102
	v_and_b32_e32 v107, 0xffff0000, v102
	v_lshlrev_b32_e32 v102, 16, v103
	v_and_b32_e32 v103, 0xffff0000, v103
	v_pk_add_f32 v[96:97], v[96:97], v[102:103]
	v_lshlrev_b32_e32 v102, 16, v104
	v_and_b32_e32 v103, 0xffff0000, v104
	v_pk_add_f32 v[102:103], v[90:91], v[102:103]
	v_lshlrev_b32_e32 v90, 16, v105
	v_and_b32_e32 v91, 0xffff0000, v105
	v_pk_add_f32 v[94:95], v[94:95], v[106:107]
	v_pk_add_f32 v[104:105], v[92:93], v[90:91]
	v_cvt_pk_bf16_f32 v90, v94, v95
	v_cvt_pk_bf16_f32 v91, v96, v97
	v_cvt_pk_bf16_f32 v92, v102, v103
	v_cvt_pk_bf16_f32 v93, v104, v105
	global_store_dwordx4 v[98:99], v[90:93], off
	s_nop 1
	v_pk_mul_f32 v[90:91], v[94:95], v[94:95]
	v_pk_mul_f32 v[92:93], v[96:97], v[96:97]
	v_pk_mul_f32 v[94:95], v[102:103], v[102:103]
	v_pk_mul_f32 v[96:97], v[104:105], v[104:105]
	s_waitcnt vmcnt(15)
	v_mov_b32_e32 v102, v184
	v_mov_b32_e32 v103, v185
	v_mov_b32_e32 v104, v186
	v_mov_b32_e32 v105, v187
	v_lshlrev_b32_e32 v106, 16, v102
	v_and_b32_e32 v107, 0xffff0000, v102
	v_lshlrev_b32_e32 v102, 16, v103
	v_and_b32_e32 v103, 0xffff0000, v103
	v_pk_add_f32 v[88:89], v[88:89], v[102:103]
	v_lshlrev_b32_e32 v102, 16, v104
	v_and_b32_e32 v103, 0xffff0000, v104
	v_pk_add_f32 v[102:103], v[82:83], v[102:103]
	v_lshlrev_b32_e32 v82, 16, v105
	v_and_b32_e32 v83, 0xffff0000, v105
	v_pk_add_f32 v[86:87], v[86:87], v[106:107]
	v_pk_add_f32 v[104:105], v[84:85], v[82:83]
	v_cvt_pk_bf16_f32 v82, v86, v87
	v_cvt_pk_bf16_f32 v83, v88, v89
	v_cvt_pk_bf16_f32 v84, v102, v103
	v_cvt_pk_bf16_f32 v85, v104, v105
	global_store_dwordx4 v[98:99], v[82:85], off offset:256
	s_nop 1
	v_pk_mul_f32 v[82:83], v[86:87], v[86:87]
	v_pk_mul_f32 v[84:85], v[88:89], v[88:89]
	v_add_f32_e32 v82, v82, v83
	v_add_f32_e32 v84, v84, v85
	v_add_f32_e32 v82, v82, v84
	v_add_f32_e32 v83, v96, v97
	v_add_f32_e32 v84, v94, v95
	v_add_f32_e32 v83, v84, v83
	v_add_f32_e32 v84, v92, v93
	v_add_f32_e32 v85, v90, v91
	v_add_f32_e32 v84, v85, v84
	v_add_f32_e32 v83, v84, v83
	v_or_b32_e32 v84, 48, v144
	v_ashrrev_i32_e32 v85, 31, v84
	v_pk_mul_f32 v[86:87], v[102:103], v[102:103]
	v_pk_mul_f32 v[88:89], v[104:105], v[104:105]
	v_lshlrev_b64 v[84:85], 13, v[84:85]
	v_add_f32_e32 v88, v88, v89
	v_add_f32_e32 v86, v86, v87
	v_lshl_add_u64 v[84:85], s[4:5], 0, v[84:85]
	v_add_f32_e32 v86, v86, v88
	v_lshl_add_u64 v[88:89], v[84:85], 0, v[148:149]
	v_add_f32_e32 v82, v82, v86
	v_add_f32_e32 v82, v83, v82
	ds_bpermute_b32 v83, v156, v82
	s_waitcnt lgkmcnt(0)
	v_add_f32_e32 v82, v82, v83
	ds_bpermute_b32 v83, v155, v82
	s_waitcnt vmcnt(15)
	v_mov_b32_e32 v84, v188
	v_mov_b32_e32 v85, v189
	v_mov_b32_e32 v86, v190
	v_mov_b32_e32 v87, v191
	v_lshlrev_b32_e32 v90, 16, v84
	v_and_b32_e32 v91, 0xffff0000, v84
	v_lshlrev_b32_e32 v84, 16, v85
	v_and_b32_e32 v85, 0xffff0000, v85
	v_pk_add_f32 v[80:81], v[80:81], v[84:85]
	v_lshlrev_b32_e32 v84, 16, v86
	v_and_b32_e32 v85, 0xffff0000, v86
	v_pk_add_f32 v[84:85], v[74:75], v[84:85]
	v_lshlrev_b32_e32 v74, 16, v87
	v_and_b32_e32 v75, 0xffff0000, v87
	v_pk_add_f32 v[78:79], v[78:79], v[90:91]
	v_pk_add_f32 v[86:87], v[76:77], v[74:75]
	v_cvt_pk_bf16_f32 v74, v78, v79
	v_cvt_pk_bf16_f32 v75, v80, v81
	v_cvt_pk_bf16_f32 v76, v84, v85
	v_cvt_pk_bf16_f32 v77, v86, v87
	global_store_dwordx4 v[88:89], v[74:77], off
	v_pk_mul_f32 v[84:85], v[84:85], v[84:85]
	v_pk_mul_f32 v[86:87], v[86:87], v[86:87]
	v_pk_mul_f32 v[78:79], v[78:79], v[78:79]
	v_pk_mul_f32 v[80:81], v[80:81], v[80:81]
	s_waitcnt vmcnt(15)
	v_mov_b32_e32 v74, v192
	v_mov_b32_e32 v75, v193
	v_mov_b32_e32 v76, v194
	v_mov_b32_e32 v77, v195
	v_lshlrev_b32_e32 v90, 16, v74
	v_and_b32_e32 v91, 0xffff0000, v74
	v_lshlrev_b32_e32 v74, 16, v75
	v_and_b32_e32 v75, 0xffff0000, v75
	v_pk_add_f32 v[72:73], v[72:73], v[74:75]
	v_lshlrev_b32_e32 v74, 16, v76
	v_and_b32_e32 v75, 0xffff0000, v76
	v_pk_add_f32 v[74:75], v[66:67], v[74:75]
	v_lshlrev_b32_e32 v66, 16, v77
	v_and_b32_e32 v67, 0xffff0000, v77
	v_pk_add_f32 v[70:71], v[70:71], v[90:91]
	v_pk_add_f32 v[76:77], v[68:69], v[66:67]
	v_cvt_pk_bf16_f32 v66, v70, v71
	v_cvt_pk_bf16_f32 v67, v72, v73
	v_cvt_pk_bf16_f32 v68, v74, v75
	v_cvt_pk_bf16_f32 v69, v76, v77
	global_store_dwordx4 v[88:89], v[66:69], off offset:256
	s_nop 1
	v_pk_mul_f32 v[66:67], v[70:71], v[70:71]
	v_pk_mul_f32 v[68:69], v[72:73], v[72:73]
	v_pk_mul_f32 v[70:71], v[74:75], v[74:75]
	v_pk_mul_f32 v[72:73], v[76:77], v[76:77]
	v_add_f32_e32 v70, v70, v71
	v_add_f32_e32 v72, v72, v73
	v_add_f32_e32 v68, v68, v69
	v_add_f32_e32 v66, v66, v67
	v_add_co_u32_e32 v74, vcc, s9, v146
	v_add_f32_e32 v70, v70, v72
	v_add_f32_e32 v66, v66, v68
	v_addc_co_u32_e32 v75, vcc, 0, v147, vcc
	v_add_f32_e32 v66, v66, v70
	v_add_f32_e32 v67, v86, v87
	v_add_f32_e32 v68, v84, v85
	v_add_f32_e32 v67, v68, v67
	v_add_f32_e32 v68, v80, v81
	v_add_f32_e32 v69, v78, v79
	v_add_f32_e32 v68, v69, v68
	v_add_f32_e32 v67, v68, v67
	v_add_f32_e32 v66, v67, v66
	ds_bpermute_b32 v67, v156, v66
	s_mov_b32 s9, 0x120000
	s_waitcnt lgkmcnt(0)
	v_add_f32_e32 v68, v66, v67
	v_lshl_add_u64 v[66:67], v[146:147], 0, s[24:25]
	s_mov_b64 s[24:25], 0x120000
	ds_bpermute_b32 v69, v155, v68
	s_waitcnt vmcnt(15)
	v_mov_b32_e32 v70, v196
	v_mov_b32_e32 v71, v197
	v_mov_b32_e32 v72, v198
	v_mov_b32_e32 v73, v199
	v_lshlrev_b32_e32 v76, 16, v70
	v_and_b32_e32 v77, 0xffff0000, v70
	v_lshlrev_b32_e32 v70, 16, v71
	v_and_b32_e32 v71, 0xffff0000, v71
	v_pk_add_f32 v[64:65], v[64:65], v[70:71]
	v_lshlrev_b32_e32 v70, 16, v72
	v_and_b32_e32 v71, 0xffff0000, v72
	v_pk_add_f32 v[70:71], v[58:59], v[70:71]
	v_lshlrev_b32_e32 v58, 16, v73
	v_and_b32_e32 v59, 0xffff0000, v73
	v_pk_add_f32 v[62:63], v[62:63], v[76:77]
	v_pk_add_f32 v[72:73], v[60:61], v[58:59]
	v_cvt_pk_bf16_f32 v58, v62, v63
	v_cvt_pk_bf16_f32 v59, v64, v65
	v_cvt_pk_bf16_f32 v60, v70, v71
	v_cvt_pk_bf16_f32 v61, v72, v73
	global_store_dwordx4 v[74:75], v[58:61], off
	v_pk_mul_f32 v[70:71], v[70:71], v[70:71]
	v_pk_mul_f32 v[72:73], v[72:73], v[72:73]
	v_pk_mul_f32 v[62:63], v[62:63], v[62:63]
	v_pk_mul_f32 v[64:65], v[64:65], v[64:65]
	s_waitcnt vmcnt(15)
	v_mov_b32_e32 v58, v200
	v_mov_b32_e32 v59, v201
	v_mov_b32_e32 v60, v202
	v_mov_b32_e32 v61, v203
	v_lshlrev_b32_e32 v74, 16, v58
	v_and_b32_e32 v75, 0xffff0000, v58
	v_lshlrev_b32_e32 v58, 16, v59
	v_and_b32_e32 v59, 0xffff0000, v59
	v_pk_add_f32 v[56:57], v[56:57], v[58:59]
	v_lshlrev_b32_e32 v58, 16, v60
	v_and_b32_e32 v59, 0xffff0000, v60
	v_pk_add_f32 v[58:59], v[50:51], v[58:59]
	v_lshlrev_b32_e32 v50, 16, v61
	v_and_b32_e32 v51, 0xffff0000, v61
	v_pk_add_f32 v[54:55], v[54:55], v[74:75]
	v_pk_add_f32 v[60:61], v[52:53], v[50:51]
	v_cvt_pk_bf16_f32 v50, v54, v55
	v_cvt_pk_bf16_f32 v51, v56, v57
	v_cvt_pk_bf16_f32 v52, v58, v59
	v_cvt_pk_bf16_f32 v53, v60, v61
	global_store_dwordx4 v[66:67], v[50:53], off offset:256
	s_nop 1
	v_pk_mul_f32 v[50:51], v[54:55], v[54:55]
	v_pk_mul_f32 v[52:53], v[56:57], v[56:57]
	v_pk_mul_f32 v[54:55], v[58:59], v[58:59]
	v_pk_mul_f32 v[56:57], v[60:61], v[60:61]
	v_add_f32_e32 v58, v72, v73
	v_add_f32_e32 v59, v70, v71
	v_add_f32_e32 v58, v59, v58
	v_add_f32_e32 v59, v64, v65
	v_add_f32_e32 v60, v62, v63
	v_add_f32_e32 v56, v56, v57
	v_add_f32_e32 v54, v54, v55
	v_add_f32_e32 v52, v52, v53
	v_add_f32_e32 v50, v50, v51
	v_add_f32_e32 v59, v60, v59
	v_add_f32_e32 v54, v54, v56
	v_add_f32_e32 v50, v50, v52
	v_add_f32_e32 v58, v59, v58
	v_add_f32_e32 v50, v50, v54
	v_add_f32_e32 v50, v58, v50
	v_add_co_u32_e32 v58, vcc, s9, v146
	ds_bpermute_b32 v51, v156, v50
	s_nop 0
	v_addc_co_u32_e32 v59, vcc, 0, v147, vcc
	s_mov_b32 s9, 0x140000
	s_waitcnt lgkmcnt(0)
	v_add_f32_e32 v52, v50, v51
	v_lshl_add_u64 v[50:51], v[146:147], 0, s[24:25]
	s_mov_b64 s[24:25], 0x140000
	ds_bpermute_b32 v53, v155, v52
	s_waitcnt vmcnt(15)
	v_mov_b32_e32 v54, v204
	v_mov_b32_e32 v55, v205
	v_mov_b32_e32 v56, v206
	v_mov_b32_e32 v57, v207
	v_lshlrev_b32_e32 v60, 16, v54
	v_and_b32_e32 v61, 0xffff0000, v54
	v_lshlrev_b32_e32 v54, 16, v55
	v_and_b32_e32 v55, 0xffff0000, v55
	v_pk_add_f32 v[48:49], v[48:49], v[54:55]
	v_lshlrev_b32_e32 v54, 16, v56
	v_and_b32_e32 v55, 0xffff0000, v56
	v_pk_add_f32 v[54:55], v[42:43], v[54:55]
	v_lshlrev_b32_e32 v42, 16, v57
	v_and_b32_e32 v43, 0xffff0000, v57
	v_pk_add_f32 v[46:47], v[46:47], v[60:61]
	v_pk_add_f32 v[56:57], v[44:45], v[42:43]
	v_cvt_pk_bf16_f32 v42, v46, v47
	v_cvt_pk_bf16_f32 v43, v48, v49
	v_cvt_pk_bf16_f32 v44, v54, v55
	v_cvt_pk_bf16_f32 v45, v56, v57
	global_store_dwordx4 v[58:59], v[42:45], off
	v_pk_mul_f32 v[54:55], v[54:55], v[54:55]
	v_pk_mul_f32 v[56:57], v[56:57], v[56:57]
	v_pk_mul_f32 v[46:47], v[46:47], v[46:47]
	v_pk_mul_f32 v[48:49], v[48:49], v[48:49]
	s_waitcnt vmcnt(15)
	v_mov_b32_e32 v42, v208
	v_mov_b32_e32 v43, v209
	v_mov_b32_e32 v44, v210
	v_mov_b32_e32 v45, v211
	v_lshlrev_b32_e32 v58, 16, v42
	v_and_b32_e32 v59, 0xffff0000, v42
	v_lshlrev_b32_e32 v42, 16, v43
	v_and_b32_e32 v43, 0xffff0000, v43
	v_pk_add_f32 v[40:41], v[40:41], v[42:43]
	v_lshlrev_b32_e32 v42, 16, v44
	v_and_b32_e32 v43, 0xffff0000, v44
	v_pk_add_f32 v[42:43], v[34:35], v[42:43]
	v_lshlrev_b32_e32 v34, 16, v45
	v_and_b32_e32 v35, 0xffff0000, v45
	v_pk_add_f32 v[38:39], v[38:39], v[58:59]
	v_pk_add_f32 v[44:45], v[36:37], v[34:35]
	v_cvt_pk_bf16_f32 v34, v38, v39
	v_cvt_pk_bf16_f32 v35, v40, v41
	v_cvt_pk_bf16_f32 v36, v42, v43
	v_cvt_pk_bf16_f32 v37, v44, v45
	global_store_dwordx4 v[50:51], v[34:37], off offset:256
	s_nop 1
	v_pk_mul_f32 v[34:35], v[38:39], v[38:39]
	v_pk_mul_f32 v[36:37], v[40:41], v[40:41]
	v_pk_mul_f32 v[38:39], v[42:43], v[42:43]
	v_pk_mul_f32 v[40:41], v[44:45], v[44:45]
	v_add_f32_e32 v42, v56, v57
	v_add_f32_e32 v43, v54, v55
	v_add_f32_e32 v42, v43, v42
	v_add_f32_e32 v43, v48, v49
	v_add_f32_e32 v44, v46, v47
	v_add_f32_e32 v40, v40, v41
	v_add_f32_e32 v38, v38, v39
	v_add_f32_e32 v36, v36, v37
	v_add_f32_e32 v34, v34, v35
	v_add_f32_e32 v43, v44, v43
	v_add_f32_e32 v38, v38, v40
	v_add_f32_e32 v34, v34, v36
	v_add_f32_e32 v42, v43, v42
	v_add_f32_e32 v34, v34, v38
	v_add_f32_e32 v34, v42, v34
	v_add_co_u32_e32 v42, vcc, s9, v146
	ds_bpermute_b32 v35, v156, v34
	s_nop 0
	v_addc_co_u32_e32 v43, vcc, 0, v147, vcc
	s_mov_b32 s9, 0x160000
	s_waitcnt lgkmcnt(0)
	v_add_f32_e32 v36, v34, v35
	v_lshl_add_u64 v[34:35], v[146:147], 0, s[24:25]
	s_mov_b64 s[24:25], 0x160000
	ds_bpermute_b32 v37, v155, v36
	s_waitcnt vmcnt(15)
	v_mov_b32_e32 v38, v216
	v_mov_b32_e32 v39, v217
	v_mov_b32_e32 v40, v218
	v_mov_b32_e32 v41, v219
	v_lshlrev_b32_e32 v44, 16, v38
	v_and_b32_e32 v45, 0xffff0000, v38
	v_lshlrev_b32_e32 v38, 16, v39
	v_and_b32_e32 v39, 0xffff0000, v39
	v_pk_add_f32 v[32:33], v[32:33], v[38:39]
	v_lshlrev_b32_e32 v38, 16, v40
	v_and_b32_e32 v39, 0xffff0000, v40
	v_pk_add_f32 v[38:39], v[26:27], v[38:39]
	v_lshlrev_b32_e32 v26, 16, v41
	v_and_b32_e32 v27, 0xffff0000, v41
	v_pk_add_f32 v[30:31], v[30:31], v[44:45]
	v_pk_add_f32 v[40:41], v[28:29], v[26:27]
	v_cvt_pk_bf16_f32 v26, v30, v31
	v_cvt_pk_bf16_f32 v27, v32, v33
	v_cvt_pk_bf16_f32 v28, v38, v39
	v_cvt_pk_bf16_f32 v29, v40, v41
	global_store_dwordx4 v[42:43], v[26:29], off
	v_pk_mul_f32 v[38:39], v[38:39], v[38:39]
	v_pk_mul_f32 v[40:41], v[40:41], v[40:41]
	v_pk_mul_f32 v[30:31], v[30:31], v[30:31]
	v_pk_mul_f32 v[32:33], v[32:33], v[32:33]
	s_waitcnt vmcnt(15)
	v_mov_b32_e32 v26, v220
	v_mov_b32_e32 v27, v221
	v_mov_b32_e32 v28, v222
	v_mov_b32_e32 v29, v223
	v_lshlrev_b32_e32 v42, 16, v26
	v_and_b32_e32 v43, 0xffff0000, v26
	v_lshlrev_b32_e32 v26, 16, v27
	v_and_b32_e32 v27, 0xffff0000, v27
	v_pk_add_f32 v[24:25], v[24:25], v[26:27]
	v_lshlrev_b32_e32 v26, 16, v28
	v_and_b32_e32 v27, 0xffff0000, v28
	v_pk_add_f32 v[26:27], v[18:19], v[26:27]
	v_lshlrev_b32_e32 v18, 16, v29
	v_and_b32_e32 v19, 0xffff0000, v29
	v_pk_add_f32 v[22:23], v[22:23], v[42:43]
	v_pk_add_f32 v[28:29], v[20:21], v[18:19]
	v_cvt_pk_bf16_f32 v18, v22, v23
	v_cvt_pk_bf16_f32 v19, v24, v25
	v_cvt_pk_bf16_f32 v20, v26, v27
	v_cvt_pk_bf16_f32 v21, v28, v29
	global_store_dwordx4 v[34:35], v[18:21], off offset:256
	s_nop 1
	v_pk_mul_f32 v[18:19], v[22:23], v[22:23]
	v_pk_mul_f32 v[20:21], v[24:25], v[24:25]
	v_pk_mul_f32 v[22:23], v[26:27], v[26:27]
	v_pk_mul_f32 v[24:25], v[28:29], v[28:29]
	v_add_f32_e32 v26, v40, v41
	v_add_f32_e32 v27, v38, v39
	v_add_f32_e32 v26, v27, v26
	v_add_f32_e32 v27, v32, v33
	v_add_f32_e32 v28, v30, v31
	v_add_f32_e32 v24, v24, v25
	v_add_f32_e32 v22, v22, v23
	v_add_f32_e32 v20, v20, v21
	v_add_f32_e32 v18, v18, v19
	v_add_f32_e32 v27, v28, v27
	v_add_f32_e32 v22, v22, v24
	v_add_f32_e32 v18, v18, v20
	v_add_f32_e32 v26, v27, v26
	v_add_f32_e32 v18, v18, v22
	v_add_f32_e32 v18, v26, v18
	v_add_co_u32_e32 v26, vcc, s9, v146
	ds_bpermute_b32 v19, v156, v18
	s_nop 0
	v_addc_co_u32_e32 v27, vcc, 0, v147, vcc
	v_cmp_lt_i32_e32 vcc, 1, v150
	s_waitcnt lgkmcnt(0)
	v_add_f32_e32 v24, v18, v19
	v_lshl_add_u64 v[18:19], v[146:147], 0, s[24:25]
	ds_bpermute_b32 v25, v155, v24
	s_waitcnt vmcnt(15)
	v_mov_b32_e32 v20, v242
	v_mov_b32_e32 v21, v243
	v_mov_b32_e32 v22, v244
	v_mov_b32_e32 v23, v245
	v_lshlrev_b32_e32 v28, 16, v20
	v_and_b32_e32 v29, 0xffff0000, v20
	v_lshlrev_b32_e32 v20, 16, v21
	v_and_b32_e32 v21, 0xffff0000, v21
	v_pk_add_f32 v[16:17], v[16:17], v[20:21]
	v_lshlrev_b32_e32 v20, 16, v22
	v_and_b32_e32 v21, 0xffff0000, v22
	v_pk_add_f32 v[20:21], v[10:11], v[20:21]
	v_lshlrev_b32_e32 v10, 16, v23
	v_and_b32_e32 v11, 0xffff0000, v23
	v_pk_add_f32 v[14:15], v[14:15], v[28:29]
	v_pk_add_f32 v[22:23], v[12:13], v[10:11]
	v_cvt_pk_bf16_f32 v10, v14, v15
	v_cvt_pk_bf16_f32 v11, v16, v17
	v_cvt_pk_bf16_f32 v12, v20, v21
	v_cvt_pk_bf16_f32 v13, v22, v23
	global_store_dwordx4 v[26:27], v[10:13], off
	v_pk_mul_f32 v[20:21], v[20:21], v[20:21]
	v_pk_mul_f32 v[22:23], v[22:23], v[22:23]
	v_pk_mul_f32 v[14:15], v[14:15], v[14:15]
	v_pk_mul_f32 v[16:17], v[16:17], v[16:17]
	s_waitcnt vmcnt(15)
	v_mov_b32_e32 v10, v246
	v_mov_b32_e32 v11, v247
	v_mov_b32_e32 v12, v248
	v_mov_b32_e32 v13, v249
	v_lshlrev_b32_e32 v26, 16, v10
	v_and_b32_e32 v27, 0xffff0000, v10
	v_lshlrev_b32_e32 v10, 16, v11
	v_and_b32_e32 v11, 0xffff0000, v11
	v_pk_add_f32 v[8:9], v[8:9], v[10:11]
	v_lshlrev_b32_e32 v10, 16, v12
	v_and_b32_e32 v11, 0xffff0000, v12
	v_pk_add_f32 v[10:11], v[2:3], v[10:11]
	v_lshlrev_b32_e32 v2, 16, v13
	v_and_b32_e32 v3, 0xffff0000, v13
	v_pk_add_f32 v[6:7], v[6:7], v[26:27]
	v_pk_add_f32 v[12:13], v[4:5], v[2:3]
	v_cvt_pk_bf16_f32 v2, v6, v7
	v_cvt_pk_bf16_f32 v3, v8, v9
	v_cvt_pk_bf16_f32 v4, v10, v11
	v_cvt_pk_bf16_f32 v5, v12, v13
	global_store_dwordx4 v[18:19], v[2:5], off offset:256
	s_nop 1
	v_pk_mul_f32 v[2:3], v[6:7], v[6:7]
	v_pk_mul_f32 v[4:5], v[8:9], v[8:9]
	v_pk_mul_f32 v[6:7], v[10:11], v[10:11]
	v_pk_mul_f32 v[8:9], v[12:13], v[12:13]
	v_add_f32_e32 v10, v22, v23
	v_add_f32_e32 v11, v20, v21
	v_add_f32_e32 v10, v11, v10
	v_add_f32_e32 v11, v16, v17
	v_add_f32_e32 v12, v14, v15
	v_add_f32_e32 v8, v8, v9
	v_add_f32_e32 v6, v6, v7
	v_add_f32_e32 v4, v4, v5
	v_add_f32_e32 v2, v2, v3
	v_add_f32_e32 v11, v12, v11
	v_add_f32_e32 v6, v6, v8
	v_add_f32_e32 v2, v2, v4
	v_add_f32_e32 v10, v11, v10
	v_add_f32_e32 v2, v2, v6
	v_add_f32_e32 v2, v10, v2
	ds_bpermute_b32 v3, v156, v2
	s_waitcnt lgkmcnt(0)
	v_add_f32_e32 v4, v2, v3
	ds_bpermute_b32 v5, v155, v4
	s_and_saveexec_b64 s[24:25], vcc
	s_xor_b64 s[24:25], exec, s[24:25]
	s_cbranch_execz .LBB0_881
	v_cmp_lt_i32_e32 vcc, 2, v150
	s_and_saveexec_b64 s[26:27], vcc
	s_xor_b64 s[26:27], exec, s[26:27]
	v_add_f32_e32 v6, v24, v25
	s_andn2_saveexec_b64 s[26:27], s[26:27]
	v_add_f32_e32 v6, v52, v53
	s_or_b64 exec, exec, s[26:27]

.LBB0_1408:
	v_and_b32_e32 v148, 64, v235
	v_xor_b32_e32 v145, 16, v235
	v_add_u32_e32 v148, 64, v148
	v_cmp_lt_i32_e32 vcc, v145, v148
	v_lshl_add_u32 v144, s50, 8, v151
	v_lshl_or_b32 v146, s49, 8, v153
	v_cndmask_b32_e32 v145, v235, v145, vcc
	v_lshlrev_b32_e32 v156, 2, v145
	v_xor_b32_e32 v145, 32, v235
	v_cmp_lt_i32_e32 vcc, v145, v148
	v_ashrrev_i32_e32 v147, 31, v146
	v_mov_b32_e32 v168, v126
	v_cndmask_b32_e32 v145, v235, v145, vcc
	v_lshlrev_b32_e32 v155, 2, v145
	v_ashrrev_i32_e32 v145, 31, v144
	v_lshlrev_b64 v[148:149], 13, v[144:145]
	v_lshl_add_u64 v[158:159], s[8:9], 0, v[148:149]
	v_lshlrev_b64 v[148:149], 1, v[146:147]
	v_lshl_add_u64 v[146:147], v[158:159], 0, v[148:149]
	global_load_dwordx4 v[158:161], v[146:147], off
	global_load_dwordx4 v[162:165], v[146:147], off offset:256
	s_mov_b64 s[100:101], 0x20000
	v_lshl_add_u64 v[224:225], v[146:147], 0, s[100:101]
	global_load_dwordx4 v[172:175], v[224:225], off
	global_load_dwordx4 v[176:179], v[224:225], off offset:256
	s_mov_b64 s[100:101], 0x40000
	v_lshl_add_u64 v[224:225], v[146:147], 0, s[100:101]
	global_load_dwordx4 v[180:183], v[224:225], off
	global_load_dwordx4 v[184:187], v[224:225], off offset:256
	s_mov_b64 s[100:101], 0x60000
	v_lshl_add_u64 v[224:225], v[146:147], 0, s[100:101]
	global_load_dwordx4 v[188:191], v[224:225], off
	global_load_dwordx4 v[192:195], v[224:225], off offset:256
	s_mov_b64 s[100:101], 0x100000
	v_lshl_add_u64 v[224:225], v[146:147], 0, s[100:101]
	global_load_dwordx4 v[196:199], v[224:225], off
	global_load_dwordx4 v[200:203], v[224:225], off offset:256
	s_mov_b64 s[100:101], 0x120000
	v_lshl_add_u64 v[224:225], v[146:147], 0, s[100:101]
	global_load_dwordx4 v[204:207], v[224:225], off
	global_load_dwordx4 v[208:211], v[224:225], off offset:256
	s_mov_b64 s[100:101], 0x140000
	v_lshl_add_u64 v[224:225], v[146:147], 0, s[100:101]
	global_load_dwordx4 v[216:219], v[224:225], off
	global_load_dwordx4 v[220:223], v[224:225], off offset:256
	s_mov_b64 s[100:101], 0x160000
	v_lshl_add_u64 v[224:225], v[146:147], 0, s[100:101]
	global_load_dwordx4 v[242:245], v[224:225], off
	global_load_dwordx4 v[246:249], v[224:225], off offset:256
	v_mov_b32_e32 v169, v118
	v_mov_b32_e32 v118, v127
	v_mov_b32_e32 v171, v120
	v_mov_b32_e32 v120, v129
	v_mov_b32_e32 v170, v128
	s_mov_b64 s[16:17], 0x100000
	s_waitcnt vmcnt(14)
	v_lshlrev_b32_e32 v166, 16, v158
	v_lshlrev_b32_e32 v167, 16, v162
	v_pk_add_f32 v[166:167], v[168:169], v[166:167]
	v_and_b32_e32 v169, 0xffff0000, v162
	v_and_b32_e32 v168, 0xffff0000, v158
	v_pk_add_f32 v[126:127], v[118:119], v[168:169]
	v_lshlrev_b32_e32 v169, 16, v163
	v_and_b32_e32 v163, 0xffff0000, v163
	v_and_b32_e32 v162, 0xffff0000, v159
	v_lshlrev_b32_e32 v168, 16, v159
	v_pk_add_f32 v[128:129], v[120:121], v[162:163]
	v_lshlrev_b32_e32 v121, 16, v164
	v_lshlrev_b32_e32 v120, 16, v160
	v_mov_b32_e32 v158, v122
	v_mov_b32_e32 v159, v114
	v_pk_add_f32 v[158:159], v[158:159], v[120:121]
	v_and_b32_e32 v121, 0xffff0000, v164
	v_and_b32_e32 v120, 0xffff0000, v160
	v_mov_b32_e32 v114, v123
	v_pk_add_f32 v[122:123], v[114:115], v[120:121]
	v_lshlrev_b32_e32 v115, 16, v165
	v_lshlrev_b32_e32 v114, 16, v161
	v_mov_b32_e32 v162, v124
	v_mov_b32_e32 v163, v116
	v_pk_add_f32 v[162:163], v[162:163], v[114:115]
	v_and_b32_e32 v115, 0xffff0000, v165
	v_and_b32_e32 v114, 0xffff0000, v161
	v_mov_b32_e32 v116, v125
	v_pk_add_f32 v[168:169], v[170:171], v[168:169]
	v_pk_add_f32 v[124:125], v[116:117], v[114:115]
	v_cvt_pk_bf16_f32 v114, v167, v127
	v_cvt_pk_bf16_f32 v115, v169, v129
	v_cvt_pk_bf16_f32 v116, v159, v123
	v_cvt_pk_bf16_f32 v117, v163, v125
	global_store_dwordx4 v[146:147], v[114:117], off offset:256
	v_cvt_pk_bf16_f32 v118, v166, v126
	v_cvt_pk_bf16_f32 v119, v168, v128
	v_pk_mul_f32 v[114:115], v[126:127], v[126:127]
	v_pk_mul_f32 v[116:117], v[128:129], v[128:129]
	v_cvt_pk_bf16_f32 v120, v158, v122
	v_cvt_pk_bf16_f32 v121, v162, v124
	v_pk_fma_f32 v[114:115], v[166:167], v[166:167], v[114:115]
	v_pk_fma_f32 v[116:117], v[168:169], v[168:169], v[116:117]
	global_store_dwordx4 v[146:147], v[118:121], off
	v_pk_add_f32 v[114:115], v[114:115], v[116:117]
	v_pk_mul_f32 v[116:117], v[122:123], v[122:123]
	v_pk_mul_f32 v[118:119], v[124:125], v[124:125]
	v_pk_fma_f32 v[116:117], v[158:159], v[158:159], v[116:117]
	v_pk_fma_f32 v[118:119], v[162:163], v[162:163], v[118:119]
	s_nop 0
	v_pk_add_f32 v[116:117], v[116:117], v[118:119]
	s_nop 0
	v_pk_add_f32 v[114:115], v[114:115], v[116:117]
	v_or_b32_e32 v116, 16, v144
	v_ashrrev_i32_e32 v117, 31, v116
	v_lshlrev_b64 v[116:117], 13, v[116:117]
	v_lshl_add_u64 v[116:117], s[8:9], 0, v[116:117]
	v_lshl_add_u64 v[120:121], v[116:117], 0, v[148:149]
	v_add_f32_e32 v114, v114, v115
	ds_bpermute_b32 v115, v156, v114
	s_waitcnt lgkmcnt(0)
	v_add_f32_e32 v114, v114, v115
	ds_bpermute_b32 v115, v155, v114
	s_waitcnt vmcnt(15)
	v_mov_b32_e32 v116, v172
	v_mov_b32_e32 v117, v173
	v_mov_b32_e32 v118, v174
	v_mov_b32_e32 v119, v175
	v_lshlrev_b32_e32 v122, 16, v116
	v_and_b32_e32 v123, 0xffff0000, v116
	v_lshlrev_b32_e32 v116, 16, v117
	v_and_b32_e32 v117, 0xffff0000, v117
	v_pk_add_f32 v[112:113], v[112:113], v[116:117]
	v_lshlrev_b32_e32 v116, 16, v118
	v_and_b32_e32 v117, 0xffff0000, v118
	v_pk_add_f32 v[116:117], v[106:107], v[116:117]
	v_lshlrev_b32_e32 v106, 16, v119
	v_and_b32_e32 v107, 0xffff0000, v119
	v_pk_add_f32 v[110:111], v[110:111], v[122:123]
	v_pk_add_f32 v[118:119], v[108:109], v[106:107]
	v_cvt_pk_bf16_f32 v106, v110, v111
	v_cvt_pk_bf16_f32 v107, v112, v113
	v_cvt_pk_bf16_f32 v108, v116, v117
	v_cvt_pk_bf16_f32 v109, v118, v119
	global_store_dwordx4 v[120:121], v[106:109], off
	v_pk_mul_f32 v[116:117], v[116:117], v[116:117]
	v_pk_mul_f32 v[118:119], v[118:119], v[118:119]
	v_pk_mul_f32 v[110:111], v[110:111], v[110:111]
	v_pk_mul_f32 v[112:113], v[112:113], v[112:113]
	s_waitcnt vmcnt(15)
	v_mov_b32_e32 v106, v176
	v_mov_b32_e32 v107, v177
	v_mov_b32_e32 v108, v178
	v_mov_b32_e32 v109, v179
	v_lshlrev_b32_e32 v122, 16, v106
	v_and_b32_e32 v123, 0xffff0000, v106
	v_lshlrev_b32_e32 v106, 16, v107
	v_and_b32_e32 v107, 0xffff0000, v107
	v_pk_add_f32 v[104:105], v[104:105], v[106:107]
	v_lshlrev_b32_e32 v106, 16, v108
	v_and_b32_e32 v107, 0xffff0000, v108
	v_pk_add_f32 v[106:107], v[98:99], v[106:107]
	v_lshlrev_b32_e32 v98, 16, v109
	v_and_b32_e32 v99, 0xffff0000, v109
	v_pk_add_f32 v[102:103], v[102:103], v[122:123]
	v_pk_add_f32 v[108:109], v[100:101], v[98:99]
	v_cvt_pk_bf16_f32 v98, v102, v103
	v_cvt_pk_bf16_f32 v99, v104, v105
	v_cvt_pk_bf16_f32 v100, v106, v107
	v_cvt_pk_bf16_f32 v101, v108, v109
	global_store_dwordx4 v[120:121], v[98:101], off offset:256
	s_nop 1
	v_pk_mul_f32 v[98:99], v[102:103], v[102:103]
	v_pk_mul_f32 v[100:101], v[104:105], v[104:105]
	v_add_f32_e32 v98, v98, v99
	v_add_f32_e32 v100, v100, v101
	v_pk_mul_f32 v[102:103], v[106:107], v[106:107]
	v_pk_mul_f32 v[104:105], v[108:109], v[108:109]
	v_add_f32_e32 v98, v98, v100
	v_add_f32_e32 v99, v118, v119
	v_add_f32_e32 v100, v116, v117
	v_add_f32_e32 v104, v104, v105
	v_add_f32_e32 v102, v102, v103
	v_add_f32_e32 v99, v100, v99
	v_add_f32_e32 v100, v112, v113
	v_add_f32_e32 v101, v110, v111
	v_add_f32_e32 v102, v102, v104
	v_add_f32_e32 v100, v101, v100
	v_add_f32_e32 v98, v98, v102
	v_add_f32_e32 v99, v100, v99
	v_add_f32_e32 v98, v99, v98
	ds_bpermute_b32 v99, v156, v98
	s_waitcnt lgkmcnt(0)
	v_add_f32_e32 v100, v98, v99
	v_or_b32_e32 v98, 32, v144
	v_ashrrev_i32_e32 v99, 31, v98
	v_lshlrev_b64 v[98:99], 13, v[98:99]
	v_lshl_add_u64 v[98:99], s[8:9], 0, v[98:99]
	v_lshl_add_u64 v[98:99], v[98:99], 0, v[148:149]
	ds_bpermute_b32 v101, v155, v100
	s_waitcnt vmcnt(15)
	v_mov_b32_e32 v102, v180
	v_mov_b32_e32 v103, v181
	v_mov_b32_e32 v104, v182
	v_mov_b32_e32 v105, v183
	v_lshlrev_b32_e32 v106, 16, v102
	v_and_b32_e32 v107, 0xffff0000, v102
	v_lshlrev_b32_e32 v102, 16, v103
	v_and_b32_e32 v103, 0xffff0000, v103
	v_pk_add_f32 v[96:97], v[96:97], v[102:103]
	v_lshlrev_b32_e32 v102, 16, v104
	v_and_b32_e32 v103, 0xffff0000, v104
	v_pk_add_f32 v[102:103], v[90:91], v[102:103]
	v_lshlrev_b32_e32 v90, 16, v105
	v_and_b32_e32 v91, 0xffff0000, v105
	v_pk_add_f32 v[94:95], v[94:95], v[106:107]
	v_pk_add_f32 v[104:105], v[92:93], v[90:91]
	v_cvt_pk_bf16_f32 v90, v94, v95
	v_cvt_pk_bf16_f32 v91, v96, v97
	v_cvt_pk_bf16_f32 v92, v102, v103
	v_cvt_pk_bf16_f32 v93, v104, v105
	global_store_dwordx4 v[98:99], v[90:93], off
	s_nop 1
	v_pk_mul_f32 v[90:91], v[94:95], v[94:95]
	v_pk_mul_f32 v[92:93], v[96:97], v[96:97]
	v_pk_mul_f32 v[94:95], v[102:103], v[102:103]
	v_pk_mul_f32 v[96:97], v[104:105], v[104:105]
	s_waitcnt vmcnt(15)
	v_mov_b32_e32 v102, v184
	v_mov_b32_e32 v103, v185
	v_mov_b32_e32 v104, v186
	v_mov_b32_e32 v105, v187
	v_lshlrev_b32_e32 v106, 16, v102
	v_and_b32_e32 v107, 0xffff0000, v102
	v_lshlrev_b32_e32 v102, 16, v103
	v_and_b32_e32 v103, 0xffff0000, v103
	v_pk_add_f32 v[88:89], v[88:89], v[102:103]
	v_lshlrev_b32_e32 v102, 16, v104
	v_and_b32_e32 v103, 0xffff0000, v104
	v_pk_add_f32 v[102:103], v[82:83], v[102:103]
	v_lshlrev_b32_e32 v82, 16, v105
	v_and_b32_e32 v83, 0xffff0000, v105
	v_pk_add_f32 v[86:87], v[86:87], v[106:107]
	v_pk_add_f32 v[104:105], v[84:85], v[82:83]
	v_cvt_pk_bf16_f32 v82, v86, v87
	v_cvt_pk_bf16_f32 v83, v88, v89
	v_cvt_pk_bf16_f32 v84, v102, v103
	v_cvt_pk_bf16_f32 v85, v104, v105
	global_store_dwordx4 v[98:99], v[82:85], off offset:256
	s_nop 1
	v_pk_mul_f32 v[82:83], v[86:87], v[86:87]
	v_pk_mul_f32 v[84:85], v[88:89], v[88:89]
	v_add_f32_e32 v82, v82, v83
	v_add_f32_e32 v84, v84, v85
	v_add_f32_e32 v82, v82, v84
	v_add_f32_e32 v83, v96, v97
	v_add_f32_e32 v84, v94, v95
	v_add_f32_e32 v83, v84, v83
	v_add_f32_e32 v84, v92, v93
	v_add_f32_e32 v85, v90, v91
	v_add_f32_e32 v84, v85, v84
	v_add_f32_e32 v83, v84, v83
	v_or_b32_e32 v84, 48, v144
	v_ashrrev_i32_e32 v85, 31, v84
	v_pk_mul_f32 v[86:87], v[102:103], v[102:103]
	v_pk_mul_f32 v[88:89], v[104:105], v[104:105]
	v_lshlrev_b64 v[84:85], 13, v[84:85]
	v_add_f32_e32 v88, v88, v89
	v_add_f32_e32 v86, v86, v87
	v_lshl_add_u64 v[84:85], s[8:9], 0, v[84:85]
	v_add_f32_e32 v86, v86, v88
	v_lshl_add_u64 v[88:89], v[84:85], 0, v[148:149]
	v_add_f32_e32 v82, v82, v86
	v_add_f32_e32 v82, v83, v82
	ds_bpermute_b32 v83, v156, v82
	s_waitcnt lgkmcnt(0)
	v_add_f32_e32 v82, v82, v83
	ds_bpermute_b32 v83, v155, v82
	s_waitcnt vmcnt(15)
	v_mov_b32_e32 v84, v188
	v_mov_b32_e32 v85, v189
	v_mov_b32_e32 v86, v190
	v_mov_b32_e32 v87, v191
	v_lshlrev_b32_e32 v90, 16, v84
	v_and_b32_e32 v91, 0xffff0000, v84
	v_lshlrev_b32_e32 v84, 16, v85
	v_and_b32_e32 v85, 0xffff0000, v85
	v_pk_add_f32 v[80:81], v[80:81], v[84:85]
	v_lshlrev_b32_e32 v84, 16, v86
	v_and_b32_e32 v85, 0xffff0000, v86
	v_pk_add_f32 v[84:85], v[74:75], v[84:85]
	v_lshlrev_b32_e32 v74, 16, v87
	v_and_b32_e32 v75, 0xffff0000, v87
	v_pk_add_f32 v[78:79], v[78:79], v[90:91]
	v_pk_add_f32 v[86:87], v[76:77], v[74:75]
	v_cvt_pk_bf16_f32 v74, v78, v79
	v_cvt_pk_bf16_f32 v75, v80, v81
	v_cvt_pk_bf16_f32 v76, v84, v85
	v_cvt_pk_bf16_f32 v77, v86, v87
	global_store_dwordx4 v[88:89], v[74:77], off
	v_pk_mul_f32 v[84:85], v[84:85], v[84:85]
	v_pk_mul_f32 v[86:87], v[86:87], v[86:87]
	v_pk_mul_f32 v[78:79], v[78:79], v[78:79]
	v_pk_mul_f32 v[80:81], v[80:81], v[80:81]
	s_waitcnt vmcnt(15)
	v_mov_b32_e32 v74, v192
	v_mov_b32_e32 v75, v193
	v_mov_b32_e32 v76, v194
	v_mov_b32_e32 v77, v195
	v_lshlrev_b32_e32 v90, 16, v74
	v_and_b32_e32 v91, 0xffff0000, v74
	v_lshlrev_b32_e32 v74, 16, v75
	v_and_b32_e32 v75, 0xffff0000, v75
	v_pk_add_f32 v[72:73], v[72:73], v[74:75]
	v_lshlrev_b32_e32 v74, 16, v76
	v_and_b32_e32 v75, 0xffff0000, v76
	v_pk_add_f32 v[74:75], v[66:67], v[74:75]
	v_lshlrev_b32_e32 v66, 16, v77
	v_and_b32_e32 v67, 0xffff0000, v77
	v_pk_add_f32 v[70:71], v[70:71], v[90:91]
	v_pk_add_f32 v[76:77], v[68:69], v[66:67]
	v_cvt_pk_bf16_f32 v66, v70, v71
	v_cvt_pk_bf16_f32 v67, v72, v73
	v_cvt_pk_bf16_f32 v68, v74, v75
	v_cvt_pk_bf16_f32 v69, v76, v77
	global_store_dwordx4 v[88:89], v[66:69], off offset:256
	s_nop 1
	v_pk_mul_f32 v[66:67], v[70:71], v[70:71]
	v_pk_mul_f32 v[68:69], v[72:73], v[72:73]
	v_add_f32_e32 v66, v66, v67
	v_add_f32_e32 v68, v68, v69
	v_pk_mul_f32 v[70:71], v[74:75], v[74:75]
	v_pk_mul_f32 v[72:73], v[76:77], v[76:77]
	v_add_f32_e32 v66, v66, v68
	v_add_f32_e32 v67, v86, v87
	v_add_f32_e32 v68, v84, v85
	v_add_f32_e32 v72, v72, v73
	v_add_f32_e32 v70, v70, v71
	v_add_f32_e32 v67, v68, v67
	v_add_f32_e32 v68, v80, v81
	v_add_f32_e32 v69, v78, v79
	v_add_f32_e32 v70, v70, v72
	v_add_f32_e32 v68, v69, v68
	v_add_f32_e32 v66, v66, v70
	v_add_f32_e32 v67, v68, v67
	v_add_f32_e32 v66, v67, v66
	ds_bpermute_b32 v67, v156, v66
	s_waitcnt lgkmcnt(0)
	v_add_f32_e32 v68, v66, v67
	v_lshl_add_u64 v[66:67], v[146:147], 0, s[16:17]
	s_mov_b32 s16, 0x100000
	v_add_co_u32_e32 v74, vcc, s16, v146
	s_mov_b64 s[16:17], 0x120000
	s_nop 0
	v_addc_co_u32_e32 v75, vcc, 0, v147, vcc
	ds_bpermute_b32 v69, v155, v68
	s_waitcnt vmcnt(15)
	v_mov_b32_e32 v70, v196
	v_mov_b32_e32 v71, v197
	v_mov_b32_e32 v72, v198
	v_mov_b32_e32 v73, v199
	v_lshlrev_b32_e32 v76, 16, v70
	v_and_b32_e32 v77, 0xffff0000, v70
	v_lshlrev_b32_e32 v70, 16, v71
	v_and_b32_e32 v71, 0xffff0000, v71
	v_pk_add_f32 v[64:65], v[64:65], v[70:71]
	v_lshlrev_b32_e32 v70, 16, v72
	v_and_b32_e32 v71, 0xffff0000, v72
	v_pk_add_f32 v[70:71], v[58:59], v[70:71]
	v_lshlrev_b32_e32 v58, 16, v73
	v_and_b32_e32 v59, 0xffff0000, v73
	v_pk_add_f32 v[62:63], v[62:63], v[76:77]
	v_pk_add_f32 v[72:73], v[60:61], v[58:59]
	v_cvt_pk_bf16_f32 v58, v62, v63
	v_cvt_pk_bf16_f32 v59, v64, v65
	v_cvt_pk_bf16_f32 v60, v70, v71
	v_cvt_pk_bf16_f32 v61, v72, v73
	global_store_dwordx4 v[74:75], v[58:61], off
	v_pk_mul_f32 v[70:71], v[70:71], v[70:71]
	v_pk_mul_f32 v[72:73], v[72:73], v[72:73]
	v_pk_mul_f32 v[62:63], v[62:63], v[62:63]
	v_pk_mul_f32 v[64:65], v[64:65], v[64:65]
	s_waitcnt vmcnt(15)
	v_mov_b32_e32 v58, v200
	v_mov_b32_e32 v59, v201
	v_mov_b32_e32 v60, v202
	v_mov_b32_e32 v61, v203
	v_lshlrev_b32_e32 v74, 16, v58
	v_and_b32_e32 v75, 0xffff0000, v58
	v_lshlrev_b32_e32 v58, 16, v59
	v_and_b32_e32 v59, 0xffff0000, v59
	v_pk_add_f32 v[56:57], v[56:57], v[58:59]
	v_lshlrev_b32_e32 v58, 16, v60
	v_and_b32_e32 v59, 0xffff0000, v60
	v_pk_add_f32 v[58:59], v[50:51], v[58:59]
	v_lshlrev_b32_e32 v50, 16, v61
	v_and_b32_e32 v51, 0xffff0000, v61
	v_pk_add_f32 v[54:55], v[54:55], v[74:75]
	v_pk_add_f32 v[60:61], v[52:53], v[50:51]
	v_cvt_pk_bf16_f32 v50, v54, v55
	v_cvt_pk_bf16_f32 v51, v56, v57
	v_cvt_pk_bf16_f32 v52, v58, v59
	v_cvt_pk_bf16_f32 v53, v60, v61
	global_store_dwordx4 v[66:67], v[50:53], off offset:256
	s_nop 1
	v_pk_mul_f32 v[50:51], v[54:55], v[54:55]
	v_pk_mul_f32 v[52:53], v[56:57], v[56:57]
	v_pk_mul_f32 v[54:55], v[58:59], v[58:59]
	v_pk_mul_f32 v[56:57], v[60:61], v[60:61]
	v_add_f32_e32 v58, v72, v73
	v_add_f32_e32 v59, v70, v71
	v_add_f32_e32 v58, v59, v58
	v_add_f32_e32 v59, v64, v65
	v_add_f32_e32 v60, v62, v63
	v_add_f32_e32 v56, v56, v57
	v_add_f32_e32 v54, v54, v55
	v_add_f32_e32 v52, v52, v53
	v_add_f32_e32 v50, v50, v51
	v_add_f32_e32 v59, v60, v59
	v_add_f32_e32 v54, v54, v56
	v_add_f32_e32 v50, v50, v52
	v_add_f32_e32 v58, v59, v58
	v_add_f32_e32 v50, v50, v54
	v_add_f32_e32 v50, v58, v50
	ds_bpermute_b32 v51, v156, v50
	s_waitcnt lgkmcnt(0)
	v_add_f32_e32 v52, v50, v51
	v_lshl_add_u64 v[50:51], v[146:147], 0, s[16:17]
	s_mov_b32 s16, 0x120000
	v_add_co_u32_e32 v58, vcc, s16, v146
	s_mov_b64 s[16:17], 0x140000
	s_nop 0
	v_addc_co_u32_e32 v59, vcc, 0, v147, vcc
	ds_bpermute_b32 v53, v155, v52
	s_waitcnt vmcnt(15)
	v_mov_b32_e32 v54, v204
	v_mov_b32_e32 v55, v205
	v_mov_b32_e32 v56, v206
	v_mov_b32_e32 v57, v207
	v_lshlrev_b32_e32 v60, 16, v54
	v_and_b32_e32 v61, 0xffff0000, v54
	v_lshlrev_b32_e32 v54, 16, v55
	v_and_b32_e32 v55, 0xffff0000, v55
	v_pk_add_f32 v[48:49], v[48:49], v[54:55]
	v_lshlrev_b32_e32 v54, 16, v56
	v_and_b32_e32 v55, 0xffff0000, v56
	v_pk_add_f32 v[54:55], v[42:43], v[54:55]
	v_lshlrev_b32_e32 v42, 16, v57
	v_and_b32_e32 v43, 0xffff0000, v57
	v_pk_add_f32 v[46:47], v[46:47], v[60:61]
	v_pk_add_f32 v[56:57], v[44:45], v[42:43]
	v_cvt_pk_bf16_f32 v42, v46, v47
	v_cvt_pk_bf16_f32 v43, v48, v49
	v_cvt_pk_bf16_f32 v44, v54, v55
	v_cvt_pk_bf16_f32 v45, v56, v57
	global_store_dwordx4 v[58:59], v[42:45], off
	v_pk_mul_f32 v[54:55], v[54:55], v[54:55]
	v_pk_mul_f32 v[56:57], v[56:57], v[56:57]
	v_pk_mul_f32 v[46:47], v[46:47], v[46:47]
	v_pk_mul_f32 v[48:49], v[48:49], v[48:49]
	s_waitcnt vmcnt(15)
	v_mov_b32_e32 v42, v208
	v_mov_b32_e32 v43, v209
	v_mov_b32_e32 v44, v210
	v_mov_b32_e32 v45, v211
	v_lshlrev_b32_e32 v58, 16, v42
	v_and_b32_e32 v59, 0xffff0000, v42
	v_lshlrev_b32_e32 v42, 16, v43
	v_and_b32_e32 v43, 0xffff0000, v43
	v_pk_add_f32 v[40:41], v[40:41], v[42:43]
	v_lshlrev_b32_e32 v42, 16, v44
	v_and_b32_e32 v43, 0xffff0000, v44
	v_pk_add_f32 v[42:43], v[34:35], v[42:43]
	v_lshlrev_b32_e32 v34, 16, v45
	v_and_b32_e32 v35, 0xffff0000, v45
	v_pk_add_f32 v[38:39], v[38:39], v[58:59]
	v_pk_add_f32 v[44:45], v[36:37], v[34:35]
	v_cvt_pk_bf16_f32 v34, v38, v39
	v_cvt_pk_bf16_f32 v35, v40, v41
	v_cvt_pk_bf16_f32 v36, v42, v43
	v_cvt_pk_bf16_f32 v37, v44, v45
	global_store_dwordx4 v[50:51], v[34:37], off offset:256
	s_nop 1
	v_pk_mul_f32 v[34:35], v[38:39], v[38:39]
	v_pk_mul_f32 v[36:37], v[40:41], v[40:41]
	v_pk_mul_f32 v[38:39], v[42:43], v[42:43]
	v_pk_mul_f32 v[40:41], v[44:45], v[44:45]
	v_add_f32_e32 v42, v56, v57
	v_add_f32_e32 v43, v54, v55
	v_add_f32_e32 v42, v43, v42
	v_add_f32_e32 v43, v48, v49
	v_add_f32_e32 v44, v46, v47
	v_add_f32_e32 v40, v40, v41
	v_add_f32_e32 v38, v38, v39
	v_add_f32_e32 v36, v36, v37
	v_add_f32_e32 v34, v34, v35
	v_add_f32_e32 v43, v44, v43
	v_add_f32_e32 v38, v38, v40
	v_add_f32_e32 v34, v34, v36
	v_add_f32_e32 v42, v43, v42
	v_add_f32_e32 v34, v34, v38
	v_add_f32_e32 v34, v42, v34
	ds_bpermute_b32 v35, v156, v34
	s_waitcnt lgkmcnt(0)
	v_add_f32_e32 v36, v34, v35
	v_lshl_add_u64 v[34:35], v[146:147], 0, s[16:17]
	s_mov_b32 s16, 0x140000
	v_add_co_u32_e32 v42, vcc, s16, v146
	s_mov_b64 s[16:17], 0x160000
	s_nop 0
	v_addc_co_u32_e32 v43, vcc, 0, v147, vcc
	ds_bpermute_b32 v37, v155, v36
	s_waitcnt vmcnt(15)
	v_mov_b32_e32 v38, v216
	v_mov_b32_e32 v39, v217
	v_mov_b32_e32 v40, v218
	v_mov_b32_e32 v41, v219
	v_lshlrev_b32_e32 v44, 16, v38
	v_and_b32_e32 v45, 0xffff0000, v38
	v_lshlrev_b32_e32 v38, 16, v39
	v_and_b32_e32 v39, 0xffff0000, v39
	v_pk_add_f32 v[32:33], v[32:33], v[38:39]
	v_lshlrev_b32_e32 v38, 16, v40
	v_and_b32_e32 v39, 0xffff0000, v40
	v_pk_add_f32 v[38:39], v[26:27], v[38:39]
	v_lshlrev_b32_e32 v26, 16, v41
	v_and_b32_e32 v27, 0xffff0000, v41
	v_pk_add_f32 v[30:31], v[30:31], v[44:45]
	v_pk_add_f32 v[40:41], v[28:29], v[26:27]
	v_cvt_pk_bf16_f32 v26, v30, v31
	v_cvt_pk_bf16_f32 v27, v32, v33
	v_cvt_pk_bf16_f32 v28, v38, v39
	v_cvt_pk_bf16_f32 v29, v40, v41
	global_store_dwordx4 v[42:43], v[26:29], off
	v_pk_mul_f32 v[38:39], v[38:39], v[38:39]
	v_pk_mul_f32 v[40:41], v[40:41], v[40:41]
	v_pk_mul_f32 v[30:31], v[30:31], v[30:31]
	v_pk_mul_f32 v[32:33], v[32:33], v[32:33]
	s_waitcnt vmcnt(15)
	v_mov_b32_e32 v26, v220
	v_mov_b32_e32 v27, v221
	v_mov_b32_e32 v28, v222
	v_mov_b32_e32 v29, v223
	v_lshlrev_b32_e32 v42, 16, v26
	v_and_b32_e32 v43, 0xffff0000, v26
	v_lshlrev_b32_e32 v26, 16, v27
	v_and_b32_e32 v27, 0xffff0000, v27
	v_pk_add_f32 v[24:25], v[24:25], v[26:27]
	v_lshlrev_b32_e32 v26, 16, v28
	v_and_b32_e32 v27, 0xffff0000, v28
	v_pk_add_f32 v[26:27], v[18:19], v[26:27]
	v_lshlrev_b32_e32 v18, 16, v29
	v_and_b32_e32 v19, 0xffff0000, v29
	v_pk_add_f32 v[22:23], v[22:23], v[42:43]
	v_pk_add_f32 v[28:29], v[20:21], v[18:19]
	v_cvt_pk_bf16_f32 v18, v22, v23
	v_cvt_pk_bf16_f32 v19, v24, v25
	v_cvt_pk_bf16_f32 v20, v26, v27
	v_cvt_pk_bf16_f32 v21, v28, v29
	global_store_dwordx4 v[34:35], v[18:21], off offset:256
	s_nop 1
	v_pk_mul_f32 v[18:19], v[22:23], v[22:23]
	v_pk_mul_f32 v[20:21], v[24:25], v[24:25]
	v_pk_mul_f32 v[22:23], v[26:27], v[26:27]
	v_pk_mul_f32 v[24:25], v[28:29], v[28:29]
	v_add_f32_e32 v26, v40, v41
	v_add_f32_e32 v27, v38, v39
	v_add_f32_e32 v26, v27, v26
	v_add_f32_e32 v27, v32, v33
	v_add_f32_e32 v28, v30, v31
	v_add_f32_e32 v24, v24, v25
	v_add_f32_e32 v22, v22, v23
	v_add_f32_e32 v20, v20, v21
	v_add_f32_e32 v18, v18, v19
	v_add_f32_e32 v27, v28, v27
	v_add_f32_e32 v22, v22, v24
	v_add_f32_e32 v18, v18, v20
	v_add_f32_e32 v26, v27, v26
	v_add_f32_e32 v18, v18, v22
	v_add_f32_e32 v18, v26, v18
	ds_bpermute_b32 v19, v156, v18
	s_waitcnt lgkmcnt(0)
	v_add_f32_e32 v24, v18, v19
	v_lshl_add_u64 v[18:19], v[146:147], 0, s[16:17]
	s_mov_b32 s16, 0x160000
	v_add_co_u32_e32 v26, vcc, s16, v146
	ds_bpermute_b32 v25, v155, v24
	s_nop 0
	v_addc_co_u32_e32 v27, vcc, 0, v147, vcc
	v_cmp_lt_i32_e32 vcc, 1, v150
	s_waitcnt vmcnt(15)
	v_mov_b32_e32 v20, v242
	v_mov_b32_e32 v21, v243
	v_mov_b32_e32 v22, v244
	v_mov_b32_e32 v23, v245
	v_lshlrev_b32_e32 v28, 16, v20
	v_and_b32_e32 v29, 0xffff0000, v20
	v_lshlrev_b32_e32 v20, 16, v21
	v_and_b32_e32 v21, 0xffff0000, v21
	v_pk_add_f32 v[16:17], v[16:17], v[20:21]
	v_lshlrev_b32_e32 v20, 16, v22
	v_and_b32_e32 v21, 0xffff0000, v22
	v_pk_add_f32 v[20:21], v[10:11], v[20:21]
	v_lshlrev_b32_e32 v10, 16, v23
	v_and_b32_e32 v11, 0xffff0000, v23
	v_pk_add_f32 v[14:15], v[14:15], v[28:29]
	v_pk_add_f32 v[22:23], v[12:13], v[10:11]
	v_cvt_pk_bf16_f32 v10, v14, v15
	v_cvt_pk_bf16_f32 v11, v16, v17
	v_cvt_pk_bf16_f32 v12, v20, v21
	v_cvt_pk_bf16_f32 v13, v22, v23
	global_store_dwordx4 v[26:27], v[10:13], off
	v_pk_mul_f32 v[20:21], v[20:21], v[20:21]
	v_pk_mul_f32 v[22:23], v[22:23], v[22:23]
	v_pk_mul_f32 v[14:15], v[14:15], v[14:15]
	v_pk_mul_f32 v[16:17], v[16:17], v[16:17]
	s_waitcnt vmcnt(15)
	v_mov_b32_e32 v10, v246
	v_mov_b32_e32 v11, v247
	v_mov_b32_e32 v12, v248
	v_mov_b32_e32 v13, v249
	v_lshlrev_b32_e32 v26, 16, v10
	v_and_b32_e32 v27, 0xffff0000, v10
	v_lshlrev_b32_e32 v10, 16, v11
	v_and_b32_e32 v11, 0xffff0000, v11
	v_pk_add_f32 v[8:9], v[8:9], v[10:11]
	v_lshlrev_b32_e32 v10, 16, v12
	v_and_b32_e32 v11, 0xffff0000, v12
	v_pk_add_f32 v[10:11], v[2:3], v[10:11]
	v_lshlrev_b32_e32 v2, 16, v13
	v_and_b32_e32 v3, 0xffff0000, v13
	v_pk_add_f32 v[6:7], v[6:7], v[26:27]
	v_pk_add_f32 v[12:13], v[4:5], v[2:3]
	v_cvt_pk_bf16_f32 v2, v6, v7
	v_cvt_pk_bf16_f32 v3, v8, v9
	v_cvt_pk_bf16_f32 v4, v10, v11
	v_cvt_pk_bf16_f32 v5, v12, v13
	global_store_dwordx4 v[18:19], v[2:5], off offset:256
	s_nop 1
	v_pk_mul_f32 v[2:3], v[6:7], v[6:7]
	v_pk_mul_f32 v[4:5], v[8:9], v[8:9]
	v_pk_mul_f32 v[6:7], v[10:11], v[10:11]
	v_pk_mul_f32 v[8:9], v[12:13], v[12:13]
	v_add_f32_e32 v10, v22, v23
	v_add_f32_e32 v11, v20, v21
	v_add_f32_e32 v10, v11, v10
	v_add_f32_e32 v11, v16, v17
	v_add_f32_e32 v12, v14, v15
	v_add_f32_e32 v8, v8, v9
	v_add_f32_e32 v6, v6, v7
	v_add_f32_e32 v4, v4, v5
	v_add_f32_e32 v2, v2, v3
	v_add_f32_e32 v11, v12, v11
	v_add_f32_e32 v6, v6, v8
	v_add_f32_e32 v2, v2, v4
	v_add_f32_e32 v10, v11, v10
	v_add_f32_e32 v2, v2, v6
	v_add_f32_e32 v2, v10, v2
	ds_bpermute_b32 v3, v156, v2
	s_waitcnt lgkmcnt(0)
	v_add_f32_e32 v4, v2, v3
	ds_bpermute_b32 v5, v155, v4
	s_and_saveexec_b64 s[16:17], vcc
	s_xor_b64 s[16:17], exec, s[16:17]
	s_cbranch_execz .LBB0_1414
	v_cmp_lt_i32_e32 vcc, 2, v150
	s_and_saveexec_b64 s[22:23], vcc
	s_xor_b64 s[22:23], exec, s[22:23]
	v_add_f32_e32 v6, v24, v25
	s_andn2_saveexec_b64 s[22:23], s[22:23]
	v_add_f32_e32 v6, v52, v53
	s_or_b64 exec, exec, s[22:23]

	.amdhsa_kernel _Z10hybrid_fwd4Args
		.amdhsa_group_segment_fixed_size 0
		.amdhsa_private_segment_fixed_size 0
		.amdhsa_kernarg_size 416
		.amdhsa_user_sgpr_count 2
		.amdhsa_user_sgpr_dispatch_ptr 0
		.amdhsa_user_sgpr_queue_ptr 0
		.amdhsa_user_sgpr_kernarg_segment_ptr 1
		.amdhsa_user_sgpr_dispatch_id 0
		.amdhsa_user_sgpr_kernarg_preload_length 0
		.amdhsa_user_sgpr_kernarg_preload_offset 0
		.amdhsa_user_sgpr_private_segment_size 0
		.amdhsa_uses_dynamic_stack 0
		.amdhsa_enable_private_segment 0
		.amdhsa_system_sgpr_workgroup_id_x 1
		.amdhsa_system_sgpr_workgroup_id_y 0
		.amdhsa_system_sgpr_workgroup_id_z 0
		.amdhsa_system_sgpr_workgroup_info 0
		.amdhsa_system_vgpr_workitem_id 0
		.amdhsa_next_free_vgpr 256
		.amdhsa_next_free_sgpr 102
		.amdhsa_accum_offset 256
		.amdhsa_reserve_vcc 1
		.amdhsa_float_round_mode_32 0
		.amdhsa_float_round_mode_16_64 0
		.amdhsa_float_denorm_mode_32 3
		.amdhsa_float_denorm_mode_16_64 3
		.amdhsa_dx10_clamp 1
		.amdhsa_ieee_mode 1
		.amdhsa_fp16_overflow 0
		.amdhsa_tg_split 0
		.amdhsa_exception_fp_ieee_invalid_op 0
		.amdhsa_exception_fp_denorm_src 0
		.amdhsa_exception_fp_ieee_div_zero 0
		.amdhsa_exception_fp_ieee_overflow 0
		.amdhsa_exception_fp_ieee_underflow 0
		.amdhsa_exception_fp_ieee_inexact 0
		.amdhsa_exception_int_div_zero 0
	.end_amdhsa_kernel

amdhsa.kernels:
  - .agpr_count:     0
    .args:
      - .offset:         0
        .size:           160
        .value_kind:     by_value
      - .offset:         160
        .size:           4
        .value_kind:     hidden_block_count_x
      - .offset:         164
        .size:           4
        .value_kind:     hidden_block_count_y
      - .offset:         168
        .size:           4
        .value_kind:     hidden_block_count_z
      - .offset:         172
        .size:           2
        .value_kind:     hidden_group_size_x
      - .offset:         174
        .size:           2
        .value_kind:     hidden_group_size_y
      - .offset:         176
        .size:           2
        .value_kind:     hidden_group_size_z
      - .offset:         178
        .size:           2
        .value_kind:     hidden_remainder_x
      - .offset:         180
        .size:           2
        .value_kind:     hidden_remainder_y
      - .offset:         182
        .size:           2
        .value_kind:     hidden_remainder_z
      - .offset:         200
        .size:           8
        .value_kind:     hidden_global_offset_x
      - .offset:         208
        .size:           8
        .value_kind:     hidden_global_offset_y
      - .offset:         216
        .size:           8
        .value_kind:     hidden_global_offset_z
      - .offset:         224
        .size:           2
        .value_kind:     hidden_grid_dims
      - .offset:         280
        .size:           4
        .value_kind:     hidden_dynamic_lds_size
    .group_segment_fixed_size: 0
    .kernarg_segment_align: 8
    .kernarg_segment_size: 416
    .language:       OpenCL C
    .language_version:
      - 2
      - 0
    .max_flat_workgroup_size: 512
    .name:           _Z10hybrid_fwd4Args
    .private_segment_fixed_size: 0
    .sgpr_count:     108
    .sgpr_spill_count: 232
    .symbol:         _Z10hybrid_fwd4Args.kd
    .uniform_work_group_size: 1
    .uses_dynamic_stack: false
    .vgpr_count:     256
    .vgpr_spill_count: 0
    .wavefront_size: 64
